# v22 plus MLA loop issues next-tile K fragment LDS reads right after the barrier, under the last 3 PV MFMAs
# baseline (speedup 1.0000x reference)
; #define MFMA(a, b, c) __builtin_amdgcn_mfma_f32_32x32x16_bf16((a), (b), (c), 0, 0, 0)
; template <int DQK, bool ALIBI>
; DI void attn_pass(const u16* __restrict__ Qp, int ldq, const u16* __restrict__ Kp, int ldk, const u16* __restrict__ VTp,
;                   int seq_start, int kt_lo, int kt_hi, int q0, float slope2, f32x16 (&O)[4], float& lsum, char* lds) {
;     ...
;     bf16x8 k0[NKS], k1[NKS], vf[2][4];
; #pragma unroll
;     for (int ks = 0; ks < NKS; ++ks) {
;       k0[ks] = *(const bf16x8*)(Ks + r * KST + ks * 16 + h * 8);
;       k1[ks] = *(const bf16x8*)(Ks + (32 + r) * KST + ks * 16 + h * 8);
;     }
;     __builtin_amdgcn_sched_barrier(0);
; #pragma unroll
;     for (int ks = 0; ks < NKS; ++ks) {
;       S0 = MFMA(k0[ks], qf[ks], S0);
;       S1 = MFMA(k1[ks], qf[ks], S1);
;     }
;     if (kt + 1 < kt_hi) ATT_LSTORE(cur ^ 1);
;     if (kt + 2 < kt_hi) ATT_GLOAD(kt + 2);
; #pragma unroll
;     for (int s = 0; s < 2; ++s)
; #pragma unroll
;       for (int db = 0; db < 4; ++db) vf[s][db] = *(const bf16x8*)(Vs + (db * 32 + r) * 72 + s * 16 + h * 8);
;     __builtin_amdgcn_sched_barrier(0);
;     bf16x8 pf[2];
;     ...
;     ATT_SOFTMAX(S0);
;     __builtin_amdgcn_sched_barrier(0);
; #pragma unroll
;     for (int s = 0; s < 2; ++s)
; #pragma unroll
;       for (int db = 0; db < 4; ++db) O[db] = MFMA(vf[s][db], pf[s], O[db]);
;     bf16x8 vg[2][4];
; #pragma unroll
;     for (int s = 0; s < 2; ++s)
; #pragma unroll
;       for (int db = 0; db < 4; ++db) vg[s][db] = *(const bf16x8*)(Vs + (db * 32 + r) * 72 + 32 + s * 16 + h * 8);
;     bf16x8 pg[2];
;     {
;       float pv[16];
; #pragma unroll
;       for (int i = 0; i < 16; ++i) pv[i] = __builtin_amdgcn_exp2f(S1[i]);
; #pragma unroll
;       for (int i = 0; i < 8; ++i) l2 += f32x2{pv[2 * i], pv[2 * i + 1]};
; #pragma unroll
;       for (int s = 0; s < 2; ++s) {
;         u32 a0 = pack2(pv[8 * s], pv[8 * s + 1]), a1 = pack2(pv[8 * s + 2], pv[8 * s + 3]);
;         u32 a2 = pack2(pv[8 * s + 4], pv[8 * s + 5]), a3 = pack2(pv[8 * s + 6], pv[8 * s + 7]);
;         u32x4 pk = {a0, a1, a2, a3};
;         pg[s] = __builtin_bit_cast(bf16x8, pk);
;       }
;     }
.LBB0_1193:
	s_add_i32 s44, s49, -2
	s_and_b32 s44, s44, 1
	s_mul_i32 s50, s44, 0x7c00
	v_add3_u32 v74, s50, v154, v161
	ds_read_b128 v[66:69], v74
	ds_read_b128 v[162:165], v74 offset:32
	ds_read_b128 v[170:173], v74 offset:64
	ds_read_b128 v[174:177], v74 offset:96
	ds_read_b128 v[194:197], v74 offset:128
	ds_read_b128 v[198:201], v74 offset:160
	ds_read_b128 v[70:73], v74 offset:6656
	ds_read_b128 v[166:169], v74 offset:6688
	ds_read_b128 v[178:181], v74 offset:6720
	ds_read_b128 v[182:185], v74 offset:6752
	ds_read_b128 v[202:205], v74 offset:6784
	ds_read_b128 v[234:237], v74 offset:6816
	s_xor_b32 s51, s44, 1
	s_mulk_i32 s51, 0x7c00
	s_waitcnt lgkmcnt(11)
	v_mfma_f32_32x32x16_bf16 v[82:97], v[66:69], v[118:121], 0
	s_waitcnt lgkmcnt(10)
	v_mfma_f32_32x32x16_bf16 v[82:97], v[162:165], v[114:117], v[82:97]
	s_waitcnt lgkmcnt(9)
	v_mfma_f32_32x32x16_bf16 v[82:97], v[170:173], v[110:113], v[82:97]
	s_waitcnt lgkmcnt(8)
	v_mfma_f32_32x32x16_bf16 v[82:97], v[174:177], v[106:109], v[82:97]
	s_waitcnt lgkmcnt(7)
	v_mfma_f32_32x32x16_bf16 v[82:97], v[194:197], v[102:105], v[82:97]
	s_waitcnt lgkmcnt(6)
	v_mfma_f32_32x32x16_bf16 v[82:97], v[198:201], v[98:101], v[82:97]
	s_waitcnt lgkmcnt(5)
	v_mfma_f32_32x32x16_bf16 v[66:81], v[70:73], v[118:121], 0
	s_waitcnt lgkmcnt(4)
	v_mfma_f32_32x32x16_bf16 v[66:81], v[166:169], v[114:117], v[66:81]
	s_branch .Lmy_mla_common
.Lmy_mla_top2:
	s_add_i32 s44, s49, -2
	s_and_b32 s44, s44, 1
	s_mul_i32 s50, s44, 0x7c00
	s_xor_b32 s51, s44, 1
	s_mulk_i32 s51, 0x7c00
	s_waitcnt lgkmcnt(11)
	v_mfma_f32_32x32x16_bf16 v[82:97], v[66:69], v[118:121], 0
	s_waitcnt lgkmcnt(10)
	v_mfma_f32_32x32x16_bf16 v[82:97], v[162:165], v[114:117], v[82:97]
	s_waitcnt lgkmcnt(2)
	v_mfma_f32_32x32x16_bf16 v[82:97], v[170:173], v[110:113], v[82:97]
	s_waitcnt lgkmcnt(1)
	v_mfma_f32_32x32x16_bf16 v[82:97], v[174:177], v[106:109], v[82:97]
	v_mfma_f32_32x32x16_bf16 v[82:97], v[194:197], v[102:105], v[82:97]
	v_mfma_f32_32x32x16_bf16 v[82:97], v[198:201], v[98:101], v[82:97]
	s_waitcnt lgkmcnt(0)
	v_mfma_f32_32x32x16_bf16 v[66:81], v[70:73], v[118:121], 0
	v_mfma_f32_32x32x16_bf16 v[66:81], v[166:169], v[114:117], v[66:81]
.Lmy_mla_common:
	v_add3_u32 v186, s50, v0, v151
	ds_read_b128 v[162:165], v186 offset:13312
	ds_read_b128 v[166:169], v186 offset:13344
	ds_read_b128 v[170:173], v186 offset:17920
	ds_read_b128 v[174:177], v186 offset:17952
	ds_read_b128 v[194:197], v186 offset:27136
	ds_read_b128 v[198:201], v186 offset:27168
	s_waitcnt lgkmcnt(8)
	v_mfma_f32_32x32x16_bf16 v[66:81], v[178:181], v[110:113], v[66:81]
	s_waitcnt lgkmcnt(7)
	v_mfma_f32_32x32x16_bf16 v[66:81], v[182:185], v[106:109], v[66:81]
	ds_read_b128 v[178:181], v186 offset:22528
	ds_read_b128 v[182:185], v186 offset:22560
	v_exp_f32_e32 v82, v82
	v_exp_f32_e32 v83, v83
	v_exp_f32_e32 v84, v84
	v_exp_f32_e32 v85, v85
	s_waitcnt lgkmcnt(9)
	v_mfma_f32_32x32x16_bf16 v[66:81], v[202:205], v[102:105], v[66:81]
	v_exp_f32_e32 v86, v86
	v_exp_f32_e32 v87, v87
	v_exp_f32_e32 v88, v88
	v_exp_f32_e32 v89, v89
	s_waitcnt lgkmcnt(8)
	v_mfma_f32_32x32x16_bf16 v[66:81], v[234:237], v[98:101], v[66:81]
	v_exp_f32_e32 v90, v90
	v_exp_f32_e32 v91, v91
	v_exp_f32_e32 v92, v92
	v_exp_f32_e32 v93, v93
	v_exp_f32_e32 v94, v94
	v_exp_f32_e32 v95, v95
	v_exp_f32_e32 v96, v96
	v_exp_f32_e32 v97, v97
	v_add_f32_e32 v148, v148, v82
	v_add_f32_e32 v149, v149, v83
	v_add_f32_e32 v148, v84, v148
	v_add_f32_e32 v149, v85, v149
	v_add_f32_e32 v148, v86, v148
	v_add_f32_e32 v149, v87, v149
	v_add_f32_e32 v148, v88, v148
	v_add_f32_e32 v149, v89, v149
	v_add_f32_e32 v148, v90, v148
	v_add_f32_e32 v149, v91, v149
	v_add_f32_e32 v148, v92, v148
	v_add_f32_e32 v149, v93, v149
	v_add_f32_e32 v148, v94, v148
	v_add_f32_e32 v149, v95, v149
	v_add_f32_e32 v148, v96, v148
	v_add_f32_e32 v149, v97, v149
	v_cvt_pk_bf16_f32 v82, v82, v83
	v_cvt_pk_bf16_f32 v83, v84, v85
	v_cvt_pk_bf16_f32 v84, v86, v87
	v_cvt_pk_bf16_f32 v85, v88, v89
	v_cvt_pk_bf16_f32 v86, v90, v91
	v_cvt_pk_bf16_f32 v87, v92, v93
	v_cvt_pk_bf16_f32 v88, v94, v95
	v_cvt_pk_bf16_f32 v89, v96, v97
	s_waitcnt lgkmcnt(7)
	v_mfma_f32_32x32x16_bf16 v[50:65], v[162:165], v[82:85], v[50:65]
	v_exp_f32_e32 v66, v66
	v_exp_f32_e32 v67, v67
	v_exp_f32_e32 v68, v68
	v_exp_f32_e32 v69, v69
	s_waitcnt lgkmcnt(5)
	v_mfma_f32_32x32x16_bf16 v[34:49], v[170:173], v[82:85], v[34:49]
	v_exp_f32_e32 v70, v70
	v_exp_f32_e32 v71, v71
	v_exp_f32_e32 v72, v72
	v_exp_f32_e32 v73, v73
	s_waitcnt lgkmcnt(3)
	v_mfma_f32_32x32x16_bf16 v[2:17], v[194:197], v[82:85], v[2:17]
	v_exp_f32_e32 v74, v74
	v_exp_f32_e32 v75, v75
	v_exp_f32_e32 v76, v76
	v_exp_f32_e32 v77, v77
	v_mfma_f32_32x32x16_bf16 v[34:49], v[174:177], v[86:89], v[34:49]
	ds_read_b128 v[174:177], v186 offset:22624
	ds_read_b128 v[170:173], v186 offset:18016
	v_exp_f32_e32 v78, v78
	v_exp_f32_e32 v79, v79
	v_exp_f32_e32 v80, v80
	v_exp_f32_e32 v81, v81
	v_mfma_f32_32x32x16_bf16 v[50:65], v[166:169], v[86:89], v[50:65]
	ds_read_b128 v[166:169], v186 offset:13408
	ds_read_b128 v[90:93], v186 offset:22592
	ds_read_b128 v[94:97], v186 offset:27200
	v_add_f32_e32 v148, v66, v148
	v_add_f32_e32 v149, v67, v149
	v_add_f32_e32 v148, v68, v148
	v_add_f32_e32 v149, v69, v149
	s_waitcnt lgkmcnt(7)
	v_mfma_f32_32x32x16_bf16 v[2:17], v[198:201], v[86:89], v[2:17]
	ds_read_b128 v[162:165], v186 offset:13376
	v_add_f32_e32 v148, v70, v148
	v_add_f32_e32 v149, v71, v149
	v_add_f32_e32 v148, v72, v148
	v_add_f32_e32 v149, v73, v149
	s_waitcnt lgkmcnt(7)
	v_mfma_f32_32x32x16_bf16 v[18:33], v[178:181], v[82:85], v[18:33]
	v_add_f32_e32 v148, v74, v148
	v_add_f32_e32 v149, v75, v149
	v_add_f32_e32 v148, v76, v148
	v_add_f32_e32 v149, v77, v149
	s_waitcnt lgkmcnt(6)
	v_mfma_f32_32x32x16_bf16 v[18:33], v[182:185], v[86:89], v[18:33]
	ds_read_b128 v[86:89], v186 offset:17984
	ds_read_b128 v[82:85], v186 offset:27232
	v_add_f32_e32 v148, v78, v148
	v_add_f32_e32 v149, v79, v149
	v_add_f32_e32 v148, v80, v148
	v_add_f32_e32 v149, v81, v149
	v_cvt_pk_bf16_f32 v66, v66, v67
	v_cvt_pk_bf16_f32 v67, v68, v69
	v_cvt_pk_bf16_f32 v68, v70, v71
	v_cvt_pk_bf16_f32 v69, v72, v73
	v_cvt_pk_bf16_f32 v70, v74, v75
	v_cvt_pk_bf16_f32 v71, v76, v77
	v_cvt_pk_bf16_f32 v72, v78, v79
	v_cvt_pk_bf16_f32 v73, v80, v81
	s_and_saveexec_b64 s[44:45], vcc
	s_cbranch_execz .LBB0_1195
	v_add3_u32 v186, s51, v155, v156
	s_waitcnt vmcnt(2)
	ds_write_b128 v186, v[122:125]

; #define MFMA(a, b, c) __builtin_amdgcn_mfma_f32_32x32x16_bf16((a), (b), (c), 0, 0, 0)
; template <int DQK, bool ALIBI>
; DI void attn_pass(const u16* __restrict__ Qp, int ldq, const u16* __restrict__ Kp, int ldk, const u16* __restrict__ VTp,
;                   int seq_start, int kt_lo, int kt_hi, int q0, float slope2, f32x16 (&O)[4], float& lsum, char* lds) {
;     ...
;     bf16x8 k0[NKS], k1[NKS], vf[2][4];
; #pragma unroll
;     for (int ks = 0; ks < NKS; ++ks) {
;       k0[ks] = *(const bf16x8*)(Ks + r * KST + ks * 16 + h * 8);
;       k1[ks] = *(const bf16x8*)(Ks + (32 + r) * KST + ks * 16 + h * 8);
;     }
;     ...
; #pragma unroll
;     for (int s = 0; s < 2; ++s)
; #pragma unroll
;       for (int db = 0; db < 4; ++db) O[db] = MFMA(vg[s][db], pg[s], O[db]);
;     __syncthreads();
.Lmy_mla_pv1:
	s_waitcnt lgkmcnt(4)
	v_mfma_f32_32x32x16_bf16 v[50:65], v[162:165], v[66:69], v[50:65]
	s_add_i32 s49, s49, 1
	s_add_i32 s44, s48, s49
	s_add_i32 s68, s68, 64
	v_lshl_add_u64 v[144:145], v[144:145], 0, s[80:81]
	v_lshl_add_u64 v[146:147], v[146:147], 0, s[80:81]
	s_cmp_lg_u32 s44, 2
	s_waitcnt lgkmcnt(3)
	v_mfma_f32_32x32x16_bf16 v[34:49], v[86:89], v[66:69], v[34:49]
	v_mfma_f32_32x32x16_bf16 v[18:33], v[90:93], v[66:69], v[18:33]
	v_mfma_f32_32x32x16_bf16 v[2:17], v[94:97], v[66:69], v[2:17]
	v_mfma_f32_32x32x16_bf16 v[50:65], v[166:169], v[70:73], v[50:65]
	s_waitcnt lgkmcnt(0)
	s_barrier
	v_add3_u32 v74, s51, v154, v161
	ds_read_b128 v[66:69], v74
	ds_read_b128 v[162:165], v74 offset:32
	ds_read_b128 v[194:197], v74 offset:128
	ds_read_b128 v[198:201], v74 offset:160
	ds_read_b128 v[166:169], v74 offset:6688
	ds_read_b128 v[178:181], v74 offset:6720
	ds_read_b128 v[182:185], v74 offset:6752
	ds_read_b128 v[202:205], v74 offset:6784
	ds_read_b128 v[234:237], v74 offset:6816
	v_mfma_f32_32x32x16_bf16 v[34:49], v[170:173], v[70:73], v[34:49]
	ds_read_b128 v[170:173], v74 offset:64
	v_mfma_f32_32x32x16_bf16 v[18:33], v[174:177], v[70:73], v[18:33]
	ds_read_b128 v[174:177], v74 offset:96
	v_mfma_f32_32x32x16_bf16 v[2:17], v[82:85], v[70:73], v[2:17]
	ds_read_b128 v[70:73], v74 offset:6656
	s_cbranch_scc1 .Lmy_mla_top2
	s_waitcnt lgkmcnt(0)
	s_branch .LBB0_1170
